# FFN1 k-loop: one global_load_dword per wave prefetches k-tile t+2 cache lines into L2 behind the LDS-DMA of tile t+1 (vmcnt(1) at loop close)
# speedup vs baseline: 1.0264x; 1.0025x over previous
.LBB0_957:
	s_setprio 3
	ds_read_b128 v[130:133], v141 offset:33792
	ds_read_b128 v[142:145], v141 offset:35840
	ds_read_b128 v[146:149], v141 offset:37888
	ds_read_b128 v[150:153], v141 offset:39936
	ds_read_b128 v[154:157], v140 offset:1024
	ds_read_b128 v[158:161], v140 offset:3072
	ds_read_b128 v[174:177], v140 offset:5120
	ds_read_b128 v[186:189], v140 offset:7168
	ds_read_b128 v[190:193], v140 offset:9216
	s_waitcnt lgkmcnt(0)
	v_mfma_f32_16x16x32_bf16 v[126:129], v[130:133], v[154:157], v[126:129]
	v_mfma_f32_16x16x32_bf16 v[122:125], v[142:145], v[154:157], v[122:125]
	v_mfma_f32_16x16x32_bf16 v[118:121], v[146:149], v[154:157], v[118:121]
	v_mfma_f32_16x16x32_bf16 v[114:117], v[150:153], v[154:157], v[114:117]
	ds_read_b128 v[154:157], v140 offset:11264
	v_mfma_f32_16x16x32_bf16 v[110:113], v[130:133], v[158:161], v[110:113]
	v_mfma_f32_16x16x32_bf16 v[106:109], v[142:145], v[158:161], v[106:109]
	v_mfma_f32_16x16x32_bf16 v[102:105], v[146:149], v[158:161], v[102:105]
	v_mfma_f32_16x16x32_bf16 v[98:101], v[150:153], v[158:161], v[98:101]
	ds_read_b128 v[158:161], v140 offset:13312
	v_mfma_f32_16x16x32_bf16 v[94:97], v[130:133], v[174:177], v[94:97]
	v_mfma_f32_16x16x32_bf16 v[90:93], v[142:145], v[174:177], v[90:93]
	v_mfma_f32_16x16x32_bf16 v[86:89], v[146:149], v[174:177], v[86:89]
	v_mfma_f32_16x16x32_bf16 v[82:85], v[150:153], v[174:177], v[82:85]
	ds_read_b128 v[174:177], v140 offset:15360
	v_mfma_f32_16x16x32_bf16 v[78:81], v[130:133], v[186:189], v[78:81]
	v_mfma_f32_16x16x32_bf16 v[74:77], v[142:145], v[186:189], v[74:77]
	v_mfma_f32_16x16x32_bf16 v[70:73], v[146:149], v[186:189], v[70:73]
	v_mfma_f32_16x16x32_bf16 v[66:69], v[150:153], v[186:189], v[66:69]
	v_mfma_f32_16x16x32_bf16 v[62:65], v[130:133], v[190:193], v[62:65]
	v_mfma_f32_16x16x32_bf16 v[58:61], v[142:145], v[190:193], v[58:61]
	v_mfma_f32_16x16x32_bf16 v[54:57], v[146:149], v[190:193], v[54:57]
	v_mfma_f32_16x16x32_bf16 v[50:53], v[150:153], v[190:193], v[50:53]
	s_waitcnt lgkmcnt(0)
	v_mfma_f32_16x16x32_bf16 v[46:49], v[130:133], v[154:157], v[46:49]
	v_mfma_f32_16x16x32_bf16 v[42:45], v[142:145], v[154:157], v[42:45]
	v_mfma_f32_16x16x32_bf16 v[38:41], v[146:149], v[154:157], v[38:41]
	v_mfma_f32_16x16x32_bf16 v[34:37], v[150:153], v[154:157], v[34:37]
	v_mfma_f32_16x16x32_bf16 v[30:33], v[130:133], v[158:161], v[30:33]
	v_mfma_f32_16x16x32_bf16 v[26:29], v[142:145], v[158:161], v[26:29]
	v_mfma_f32_16x16x32_bf16 v[22:25], v[146:149], v[158:161], v[22:25]
	v_mfma_f32_16x16x32_bf16 v[18:21], v[150:153], v[158:161], v[18:21]
	v_mfma_f32_16x16x32_bf16 v[14:17], v[130:133], v[174:177], v[14:17]
	v_mfma_f32_16x16x32_bf16 v[10:13], v[142:145], v[174:177], v[10:13]
	v_mfma_f32_16x16x32_bf16 v[6:9], v[146:149], v[174:177], v[6:9]
	v_mfma_f32_16x16x32_bf16 v[2:5], v[150:153], v[174:177], v[2:5]
	s_setprio 0
	s_add_i32 s77, s77, 64
	s_add_i32 s76, s76, 0x10000
	s_cmpk_eq_i32 s77, 0x3c0
	s_cbranch_scc1 .Lpf_f1_last
	s_waitcnt vmcnt(1)
	s_barrier
	s_branch .Lpf_f1_cont
.Lpf_f1_last:
	s_waitcnt vmcnt(0)
	s_barrier
	s_branch .LBB0_962
.Lpf_f1_cont:
.LBB0_958:
	v_add_u32_e32 v130, s77, v139
	s_and_b32 s89, s76, 0x10000
	s_andn2_b64 vcc, exec, s[58:59]
	v_add_u32_e32 v0, 64, v130
	v_add_u32_e32 v134, 0x10040, v130
	v_add_u32_e32 v132, 0x20040, v130
	v_add_u32_e32 v130, 0x30040, v130
	s_cbranch_vccnz .LBB0_960
	s_xor_b32 s91, s89, 0x10000
	v_add_u32_e32 v144, s91, v172
	v_add_u32_e32 v131, 0x8000, v144
	v_lshlrev_b64 v[140:141], 1, v[0:1]
	v_readfirstlane_b32 s91, v144
	v_lshl_add_u64 v[142:143], s[86:87], 0, v[140:141]
	s_mov_b32 m0, s91
	v_readfirstlane_b32 s91, v131
	global_load_lds_dwordx4 v[142:143], off
	v_lshl_add_u64 v[140:141], s[96:97], 0, v[140:141]
	s_mov_b32 m0, s91
	v_mov_b32_e32 v135, v1
	v_add_u32_e32 v131, 0x2000, v144
	global_load_lds_dwordx4 v[140:141], off
	v_lshlrev_b64 v[140:141], 1, v[134:135]
	v_readfirstlane_b32 s91, v131
	v_add_u32_e32 v131, 0xa000, v144
	v_lshl_add_u64 v[142:143], s[86:87], 0, v[140:141]
	s_mov_b32 m0, s91
	v_readfirstlane_b32 s91, v131
	global_load_lds_dwordx4 v[142:143], off
	v_lshl_add_u64 v[140:141], s[96:97], 0, v[140:141]
	s_mov_b32 m0, s91
	v_mov_b32_e32 v133, v1
	v_add_u32_e32 v131, 0x4000, v144
	global_load_lds_dwordx4 v[140:141], off
	v_lshlrev_b64 v[140:141], 1, v[132:133]
	v_readfirstlane_b32 s91, v131
	v_add_u32_e32 v131, 0xc000, v144
	v_lshl_add_u64 v[142:143], s[86:87], 0, v[140:141]
	s_mov_b32 m0, s91
	v_readfirstlane_b32 s91, v131
	global_load_lds_dwordx4 v[142:143], off
	v_lshl_add_u64 v[140:141], s[96:97], 0, v[140:141]
	s_mov_b32 m0, s91
	v_mov_b32_e32 v131, v1
	global_load_lds_dwordx4 v[140:141], off
	v_lshlrev_b64 v[140:141], 1, v[130:131]
	v_add_u32_e32 v131, 0x6000, v144
	v_lshl_add_u64 v[142:143], s[86:87], 0, v[140:141]
	v_readfirstlane_b32 s91, v131
	v_add_u32_e32 v131, 0xe000, v144
	s_mov_b32 m0, s91
	v_readfirstlane_b32 s91, v131
	global_load_lds_dwordx4 v[142:143], off
	v_lshl_add_u64 v[140:141], s[96:97], 0, v[140:141]
	s_mov_b32 m0, s91
	s_nop 0
	global_load_lds_dwordx4 v[140:141], off
	s_cmpk_eq_i32 s77, 0x380
	s_cbranch_scc1 .Lpf_skip_f1a
	v_readfirstlane_b32 s14, v162
	v_lshrrev_b32_e32 v202, 7, v162
	v_bfe_u32 v203, v162, 4, 2
	v_lshl_add_u32 v202, v203, 2, v202
	v_and_b32_e32 v203, 15, v162
	v_lshl_add_u32 v202, v202, 4, v203
	s_lshl_b32 s15, s77, 1
	s_addk_i32 s15, 0x100
	v_lshl_add_u32 v202, v202, 11, s15
	s_bitcmp1_b32 s14, 6
	s_cselect_b32 s16, s96, s86
	s_cselect_b32 s17, s97, s87
	global_load_dword v204, v202, s[16:17]
.Lpf_skip_f1a:
.LBB0_960:
	s_add_i32 s91, s89, 0x400
	v_add_u32_e32 v131, s91, v137
	v_add_u32_e32 v133, s91, v138
	s_setprio 3
	v_add_u32_e32 v141, v133, v136
	ds_read_b128 v[142:145], v141 offset:32768
	ds_read_b128 v[146:149], v141 offset:34816
	ds_read_b128 v[150:153], v141 offset:36864
	ds_read_b128 v[154:157], v141 offset:38912
	v_add_u32_e32 v140, v131, v136
	ds_read_b128 v[158:161], v140
	ds_read_b128 v[174:177], v140 offset:2048
	ds_read_b128 v[186:189], v140 offset:4096
	ds_read_b128 v[190:193], v140 offset:6144
	ds_read_b128 v[194:197], v140 offset:8192
	s_waitcnt lgkmcnt(0)
	v_mfma_f32_16x16x32_bf16 v[126:129], v[142:145], v[158:161], v[126:129]
	v_mfma_f32_16x16x32_bf16 v[122:125], v[146:149], v[158:161], v[122:125]
	v_mfma_f32_16x16x32_bf16 v[118:121], v[150:153], v[158:161], v[118:121]
	v_mfma_f32_16x16x32_bf16 v[114:117], v[154:157], v[158:161], v[114:117]
	ds_read_b128 v[158:161], v140 offset:10240
	v_mfma_f32_16x16x32_bf16 v[110:113], v[142:145], v[174:177], v[110:113]
	v_mfma_f32_16x16x32_bf16 v[106:109], v[146:149], v[174:177], v[106:109]
	v_mfma_f32_16x16x32_bf16 v[102:105], v[150:153], v[174:177], v[102:105]
	v_mfma_f32_16x16x32_bf16 v[98:101], v[154:157], v[174:177], v[98:101]
	ds_read_b128 v[174:177], v140 offset:12288
	v_mfma_f32_16x16x32_bf16 v[94:97], v[142:145], v[186:189], v[94:97]
	v_mfma_f32_16x16x32_bf16 v[90:93], v[146:149], v[186:189], v[90:93]
	v_mfma_f32_16x16x32_bf16 v[86:89], v[150:153], v[186:189], v[86:89]
	v_mfma_f32_16x16x32_bf16 v[82:85], v[154:157], v[186:189], v[82:85]
	ds_read_b128 v[186:189], v140 offset:14336
	v_mfma_f32_16x16x32_bf16 v[78:81], v[142:145], v[190:193], v[78:81]
	v_mfma_f32_16x16x32_bf16 v[74:77], v[146:149], v[190:193], v[74:77]
	v_mfma_f32_16x16x32_bf16 v[70:73], v[150:153], v[190:193], v[70:73]
	v_mfma_f32_16x16x32_bf16 v[66:69], v[154:157], v[190:193], v[66:69]
	v_mfma_f32_16x16x32_bf16 v[62:65], v[142:145], v[194:197], v[62:65]
	v_mfma_f32_16x16x32_bf16 v[58:61], v[146:149], v[194:197], v[58:61]
	v_mfma_f32_16x16x32_bf16 v[54:57], v[150:153], v[194:197], v[54:57]
	v_mfma_f32_16x16x32_bf16 v[50:53], v[154:157], v[194:197], v[50:53]
	s_waitcnt lgkmcnt(0)
	v_mfma_f32_16x16x32_bf16 v[46:49], v[142:145], v[158:161], v[46:49]
	v_mfma_f32_16x16x32_bf16 v[42:45], v[146:149], v[158:161], v[42:45]
	v_mfma_f32_16x16x32_bf16 v[38:41], v[150:153], v[158:161], v[38:41]
	v_mfma_f32_16x16x32_bf16 v[34:37], v[154:157], v[158:161], v[34:37]
	v_mfma_f32_16x16x32_bf16 v[30:33], v[142:145], v[174:177], v[30:33]
	v_mfma_f32_16x16x32_bf16 v[26:29], v[146:149], v[174:177], v[26:29]
	v_mfma_f32_16x16x32_bf16 v[22:25], v[150:153], v[174:177], v[22:25]
	v_mfma_f32_16x16x32_bf16 v[18:21], v[154:157], v[174:177], v[18:21]
	v_mfma_f32_16x16x32_bf16 v[14:17], v[142:145], v[186:189], v[14:17]
	v_mfma_f32_16x16x32_bf16 v[10:13], v[146:149], v[186:189], v[10:13]
	v_mfma_f32_16x16x32_bf16 v[6:9], v[150:153], v[186:189], v[6:9]
	v_mfma_f32_16x16x32_bf16 v[2:5], v[154:157], v[186:189], v[2:5]
	s_setprio 0
	s_andn2_b64 vcc, exec, s[94:95]
	s_cbranch_vccnz .LBB0_957
	s_xor_b32 s89, s89, 0x10000
	v_add_u32_e32 v146, s89, v172
	v_add_u32_e32 v131, 0x8000, v146
	v_lshlrev_b64 v[142:143], 1, v[0:1]
	v_readfirstlane_b32 s89, v146
	v_lshl_add_u64 v[144:145], s[86:87], 0, v[142:143]
	s_mov_b32 m0, s89
	v_readfirstlane_b32 s89, v131
	v_mov_b32_e32 v135, v1
	v_add_u32_e32 v0, 0x2000, v146
	global_load_lds_dwordx4 v[144:145], off
	v_lshl_add_u64 v[142:143], s[96:97], 0, v[142:143]
	s_mov_b32 m0, s89
	v_lshlrev_b64 v[134:135], 1, v[134:135]
	v_readfirstlane_b32 s89, v0
	v_add_u32_e32 v0, 0xa000, v146
	global_load_lds_dwordx4 v[142:143], off
	v_lshl_add_u64 v[142:143], s[86:87], 0, v[134:135]
	s_mov_b32 m0, s89
	v_readfirstlane_b32 s89, v0
	v_mov_b32_e32 v133, v1
	v_add_u32_e32 v0, 0x4000, v146
	global_load_lds_dwordx4 v[142:143], off
	v_lshl_add_u64 v[134:135], s[96:97], 0, v[134:135]
	s_mov_b32 m0, s89
	v_lshlrev_b64 v[132:133], 1, v[132:133]
	v_readfirstlane_b32 s89, v0
	v_add_u32_e32 v0, 0xc000, v146
	global_load_lds_dwordx4 v[134:135], off
	v_lshl_add_u64 v[134:135], s[86:87], 0, v[132:133]
	s_mov_b32 m0, s89
	v_readfirstlane_b32 s89, v0
	v_mov_b32_e32 v131, v1
	v_add_u32_e32 v0, 0x6000, v146
	global_load_lds_dwordx4 v[134:135], off
	v_lshl_add_u64 v[132:133], s[96:97], 0, v[132:133]
	s_mov_b32 m0, s89
	v_lshlrev_b64 v[130:131], 1, v[130:131]
	v_readfirstlane_b32 s89, v0
	v_add_u32_e32 v0, 0xe000, v146
	global_load_lds_dwordx4 v[132:133], off
	v_lshl_add_u64 v[132:133], s[86:87], 0, v[130:131]
	s_mov_b32 m0, s89
	v_readfirstlane_b32 s89, v0
	global_load_lds_dwordx4 v[132:133], off
	v_lshl_add_u64 v[130:131], s[96:97], 0, v[130:131]
	s_mov_b32 m0, s89
	s_nop 0
	global_load_lds_dwordx4 v[130:131], off
	s_cmpk_eq_i32 s77, 0x380
	s_cbranch_scc1 .Lpf_skip_f1b
	v_readfirstlane_b32 s14, v162
	v_lshrrev_b32_e32 v202, 7, v162
	v_bfe_u32 v203, v162, 4, 2
	v_lshl_add_u32 v202, v203, 2, v202
	v_and_b32_e32 v203, 15, v162
	v_lshl_add_u32 v202, v202, 4, v203
	s_lshl_b32 s15, s77, 1
	s_addk_i32 s15, 0x100
	v_lshl_add_u32 v202, v202, 11, s15
	s_bitcmp1_b32 s14, 6
	s_cselect_b32 s16, s96, s86
	s_cselect_b32 s17, s97, s87
	global_load_dword v204, v202, s[16:17]
.Lpf_skip_f1b:
	s_branch .LBB0_957
.LBB0_962:
	s_lshl_b64 s[76:77], s[54:55], 11
	s_add_u32 s58, s40, s92
	s_addc_u32 s59, s60, s93
	s_cmp_gt_i32 s54, -1
	s_cselect_b64 s[86:87], -1, 0
	s_add_u32 s92, s73, s76
	s_addc_u32 s93, s74, s77
	s_xor_b64 s[76:77], s[94:95], -1
	s_and_b64 s[76:77], s[86:87], s[76:77]
	s_andn2_b64 vcc, exec, s[76:77]
	s_cbranch_vccnz .LBB0_964
	v_mov_b32_e32 v167, v1
	v_add_u32_e32 v0, 0x8000, v172
	v_lshlrev_b64 v[130:131], 1, v[166:167]
	v_readfirstlane_b32 s54, v172
	v_lshl_add_u64 v[132:133], s[92:93], 0, v[130:131]
	s_mov_b32 m0, s54
	v_readfirstlane_b32 s54, v0
	global_load_lds_dwordx4 v[132:133], off
	v_lshl_add_u64 v[130:131], s[58:59], 0, v[130:131]
	s_mov_b32 m0, s54
	v_add_u32_e32 v0, 0x10000, v166
	global_load_lds_dwordx4 v[130:131], off
	v_lshlrev_b64 v[130:131], 1, v[0:1]
	v_add_u32_e32 v0, 0x2000, v172
	v_lshl_add_u64 v[132:133], s[92:93], 0, v[130:131]
	v_readfirstlane_b32 s54, v0
	v_add_u32_e32 v0, 0xa000, v172
	s_mov_b32 m0, s54
	v_readfirstlane_b32 s54, v0
	global_load_lds_dwordx4 v[132:133], off
	v_lshl_add_u64 v[130:131], s[58:59], 0, v[130:131]
	s_mov_b32 m0, s54
	v_add_u32_e32 v0, 0x20000, v166
	global_load_lds_dwordx4 v[130:131], off
	v_lshlrev_b64 v[130:131], 1, v[0:1]
	v_add_u32_e32 v0, 0x4000, v172
	v_lshl_add_u64 v[132:133], s[92:93], 0, v[130:131]
	v_readfirstlane_b32 s54, v0
	v_add_u32_e32 v0, 0xc000, v172
	s_mov_b32 m0, s54
	v_readfirstlane_b32 s54, v0
	global_load_lds_dwordx4 v[132:133], off
	v_lshl_add_u64 v[130:131], s[58:59], 0, v[130:131]
	s_mov_b32 m0, s54
	v_add_u32_e32 v0, 0x30000, v166
	global_load_lds_dwordx4 v[130:131], off
	v_lshlrev_b64 v[130:131], 1, v[0:1]
	v_add_u32_e32 v0, 0x6000, v172
	v_lshl_add_u64 v[132:133], s[92:93], 0, v[130:131]
	v_readfirstlane_b32 s54, v0
	v_add_u32_e32 v0, 0xe000, v172
	s_mov_b32 m0, s54
	v_readfirstlane_b32 s54, v0
	global_load_lds_dwordx4 v[132:133], off
	v_lshl_add_u64 v[130:131], s[58:59], 0, v[130:131]
	s_mov_b32 m0, s54
	s_nop 0
	global_load_lds_dwordx4 v[130:131], off
